# attn merge epilogue: all 32 loads of the 8 groups hoisted (4 slots x 2 rounds) instead of 8 serial round trips
# speedup vs baseline: 1.0046x; 1.0011x over previous
; DI unsigned pk2(float lo, float hi) { const f32x2_t v = {lo, hi}; const bf16x2_t b = __builtin_convertvector(v, bf16x2_t); return __builtin_bit_cast(unsigned, b); }
; DI float sigmoidf_(float x) { return __builtin_amdgcn_rcpf(1.f + __builtin_amdgcn_exp2f(fminf(-x * LOG2E, 126.f))); }
; template <int DV>
; DI void attn_unit(const int wv, const Args& A, LAS unsigned char* lds, int b, int g, int qb, int dry) {
;     ...
;         const float sc = g2 / fmaxf(l, 1e-30f);
; #pragma unroll
;         for (int i = 0; i < 16; ++i) { O[0][i] = ypark[i * 64] + sc * O[0][i]; O[1][i] = ypark[(16 + i) * 64] + sc * O[1][i]; }
;     }
;     if (!(dry & 32))
;     {
;         bf16* Yb = (bf16*)A.out; const bf16* GMA = (const bf16*)(ws + WS_GMA);
; #pragma unroll
;         for (int mt = 0; mt < 2; ++mt)
; #pragma unroll
;             for (int v = 0; v < 4; ++v) {
;                 const size_t idx = tokrow * DM + head * 64 + mt * 32 + 8 * v + 4 * c.h;
;                 const u32x2 yr = *(const u32x2*)(Yb + idx), gm = *(const u32x2*)(GMA + idx), ct = *(const u32x2*)((const bf16*)(ws + WS_CT) + idx);
;                 const f32x4 cr = *(const f32x4*)((const float*)(ws + WS_CARRY) + ((size_t)b * 64 + (c.t >> 7)) * DM + head * 64 + mt * 32 + 8 * v + 4 * c.h);
;                 const float o0 = bflo(yr.x) + bflo(ct.x) * cr[0] + sigmoidf_(bflo(gm.x)) * O[mt][4 * v], o1 = bfhi(yr.x) + bfhi(ct.x) * cr[1] + sigmoidf_(bfhi(gm.x)) * O[mt][4 * v + 1];
;                 const float o2 = bflo(yr.y) + bflo(ct.y) * cr[2] + sigmoidf_(bflo(gm.y)) * O[mt][4 * v + 2], o3 = bfhi(yr.y) + bfhi(ct.y) * cr[3] + sigmoidf_(bfhi(gm.y)) * O[mt][4 * v + 3];
;                 *(u32x2*)(((dry & 1) ? (bf16*)(ws + 832 * MiB) : Yb) + idx) = (u32x2){pk2(o0, o1), pk2(o2, o3)};
.LBB0_789:
	s_waitcnt vmcnt(0)
	v_or_b32_e32 v0, v211, v154
	v_or_b32_e32 v164, v0, v164
	v_lshlrev_b64 v[10:11], 1, v[164:165]
	v_readlane_b32 s8, v254, 2
	v_readlane_b32 s9, v254, 3
	v_lshl_add_u64 v[4:5], s[64:65], 0, v[10:11]
	v_lshl_add_u64 v[6:7], s[66:67], 0, v[10:11]
	s_nop 0
	v_lshl_add_u64 v[0:1], s[8:9], 0, v[10:11]
	s_lshr_b32 s62, s91, 7
	s_lshl_b32 s6, s45, 18
	v_readlane_b32 s7, v254, 59
	s_nop 3
	s_add_u32 s8, s7, s6
	s_addc_u32 s9, s89, 0
	s_lshl_b64 s[6:7], s[62:63], 12
	s_add_u32 s6, s8, s6
	v_lshlrev_b32_e32 v8, 2, v211
	v_mov_b32_e32 v9, v2
	s_addc_u32 s7, s9, s7
	v_mov_b32_e32 v155, v2
	v_lshl_add_u64 v[8:9], s[6:7], 0, v[8:9]
	v_lshl_add_u64 v[12:13], v[154:155], 2, v[8:9]
	global_load_dwordx2 v[112:113], v[4:5], off
	global_load_dwordx2 v[114:115], v[6:7], off
	global_load_dwordx2 v[116:117], v[0:1], off
	global_load_dwordx4 v[120:123], v[12:13], off
	global_load_dwordx2 v[124:125], v[4:5], off offset:16
	global_load_dwordx2 v[126:127], v[6:7], off offset:16
	global_load_dwordx2 v[128:129], v[0:1], off offset:16
	global_load_dwordx4 v[132:135], v[12:13], off offset:32
	global_load_dwordx2 v[232:233], v[4:5], off offset:32
	global_load_dwordx2 v[234:235], v[6:7], off offset:32
	global_load_dwordx2 v[236:237], v[0:1], off offset:32
	global_load_dwordx4 v[240:243], v[12:13], off offset:64
	global_load_dwordx2 v[244:245], v[4:5], off offset:48
	global_load_dwordx2 v[246:247], v[6:7], off offset:48
	global_load_dwordx2 v[248:249], v[0:1], off offset:48
	global_load_dwordx4 v[250:253], v[12:13], off offset:96
	v_lshlrev_b32_e32 v3, 16, v163
	v_mul_f32_e32 v3, 0xbfb8aa3b, v3
	v_min_f32_e32 v3, 0x42fc0000, v3
	v_exp_f32_e32 v3, v3
	v_readlane_b32 s10, v254, 4
	v_readlane_b32 s11, v254, 5
	v_add_f32_e32 v3, 1.0, v3
	v_rcp_f32_e32 v3, v3
	s_nop 0
	v_div_scale_f32 v8, s[6:7], v32, v32, v3
	v_rcp_f32_e32 v9, v8
	v_div_scale_f32 v33, vcc, v3, v32, v3
	s_mov_b64 s[6:7], 0
	v_fma_f32 v48, -v8, v9, 1.0
	v_fmac_f32_e32 v9, v48, v9
	v_mul_f32_e32 v48, v33, v9
	v_fma_f32 v49, -v8, v48, v33
	v_fmac_f32_e32 v48, v49, v9
	v_fma_f32 v8, -v8, v48, v33
	v_div_fmas_f32 v8, v8, v9, v48
	v_div_fixup_f32 v8, v8, v32, v3
	ds_read2st64_b32 v[40:41], v137 offset1:1
	ds_read2st64_b32 v[42:43], v137 offset0:2 offset1:3
	s_waitcnt vmcnt(12)
	v_lshlrev_b32_e32 v3, 16, v112
	v_and_b32_e32 v9, 0xffff0000, v112
	v_lshlrev_b32_e32 v38, 16, v113
	v_and_b32_e32 v39, 0xffff0000, v113
	v_mul_f32_e32 v3, 0xbfb8aa3b, v3
	v_mul_f32_e32 v9, 0xbfb8aa3b, v9
	v_mul_f32_e32 v38, 0xbfb8aa3b, v38
	v_mul_f32_e32 v39, 0xbfb8aa3b, v39
	v_min_f32_e32 v3, 0x42fc0000, v3
	v_min_f32_e32 v9, 0x42fc0000, v9
	v_min_f32_e32 v38, 0x42fc0000, v38
	v_min_f32_e32 v39, 0x42fc0000, v39
	v_exp_f32_e32 v3, v3
	v_exp_f32_e32 v9, v9
	v_exp_f32_e32 v38, v38
	v_exp_f32_e32 v39, v39
	v_add_f32_e32 v3, 1.0, v3
	v_add_f32_e32 v9, 1.0, v9
	v_add_f32_e32 v50, 1.0, v38
	v_add_f32_e32 v51, 1.0, v39
	v_rcp_f32_e32 v38, v3
	v_rcp_f32_e32 v39, v9
	v_rcp_f32_e32 v50, v50
	v_rcp_f32_e32 v51, v51
	v_lshlrev_b32_e32 v48, 16, v114
	v_and_b32_e32 v49, 0xffff0000, v114
	v_lshlrev_b32_e32 v36, 16, v115
	v_and_b32_e32 v37, 0xffff0000, v115
	v_lshlrev_b32_e32 v44, 16, v116
	v_and_b32_e32 v45, 0xffff0000, v116
	v_lshlrev_b32_e32 v46, 16, v117
	v_and_b32_e32 v47, 0xffff0000, v117
	s_waitcnt lgkmcnt(0)
	v_pk_fma_f32 v[34:35], v[8:9], v[64:65], v[40:41] op_sel_hi:[0,1,1]
	v_pk_fma_f32 v[40:41], v[8:9], v[66:67], v[42:43] op_sel_hi:[0,1,1]
	v_pk_fma_f32 v[120:121], v[120:121], v[48:49], v[44:45]
	v_pk_fma_f32 v[122:123], v[122:123], v[36:37], v[46:47]
	v_pk_fma_f32 v[120:121], v[34:35], v[38:39], v[120:121]
	v_pk_fma_f32 v[122:123], v[40:41], v[50:51], v[122:123]
	v_cvt_pk_bf16_f32 v120, v120, v121
	v_cvt_pk_bf16_f32 v121, v122, v123
	global_store_dwordx2 v[0:1], v[120:121], off
	global_load_dwordx2 v[112:113], v[4:5], off offset:64
	global_load_dwordx2 v[114:115], v[6:7], off offset:64
	global_load_dwordx2 v[116:117], v[0:1], off offset:64
	global_load_dwordx4 v[120:123], v[12:13], off offset:128
	ds_read2st64_b32 v[40:41], v137 offset0:4 offset1:5
	ds_read2st64_b32 v[42:43], v137 offset0:6 offset1:7
	s_waitcnt vmcnt(13)
	v_lshlrev_b32_e32 v3, 16, v124
	v_and_b32_e32 v9, 0xffff0000, v124
	v_lshlrev_b32_e32 v38, 16, v125
	v_and_b32_e32 v39, 0xffff0000, v125
	v_mul_f32_e32 v3, 0xbfb8aa3b, v3
	v_mul_f32_e32 v9, 0xbfb8aa3b, v9
	v_mul_f32_e32 v38, 0xbfb8aa3b, v38
	v_mul_f32_e32 v39, 0xbfb8aa3b, v39
	v_min_f32_e32 v3, 0x42fc0000, v3
	v_min_f32_e32 v9, 0x42fc0000, v9
	v_min_f32_e32 v38, 0x42fc0000, v38
	v_min_f32_e32 v39, 0x42fc0000, v39
	v_exp_f32_e32 v3, v3
	v_exp_f32_e32 v9, v9
	v_exp_f32_e32 v38, v38
	v_exp_f32_e32 v39, v39
	v_add_f32_e32 v3, 1.0, v3
	v_add_f32_e32 v9, 1.0, v9
	v_add_f32_e32 v50, 1.0, v38
	v_add_f32_e32 v51, 1.0, v39
	v_rcp_f32_e32 v38, v3
	v_rcp_f32_e32 v39, v9
	v_rcp_f32_e32 v50, v50
	v_rcp_f32_e32 v51, v51
	v_lshlrev_b32_e32 v48, 16, v126
	v_and_b32_e32 v49, 0xffff0000, v126
	v_lshlrev_b32_e32 v36, 16, v127
	v_and_b32_e32 v37, 0xffff0000, v127
	v_lshlrev_b32_e32 v44, 16, v128
	v_and_b32_e32 v45, 0xffff0000, v128
	v_lshlrev_b32_e32 v46, 16, v129
	v_and_b32_e32 v47, 0xffff0000, v129
	s_waitcnt lgkmcnt(0)
	v_pk_fma_f32 v[34:35], v[8:9], v[68:69], v[40:41] op_sel_hi:[0,1,1]
	v_pk_fma_f32 v[40:41], v[8:9], v[70:71], v[42:43] op_sel_hi:[0,1,1]
	v_pk_fma_f32 v[132:133], v[132:133], v[48:49], v[44:45]
	v_pk_fma_f32 v[134:135], v[134:135], v[36:37], v[46:47]
	v_pk_fma_f32 v[132:133], v[34:35], v[38:39], v[132:133]
	v_pk_fma_f32 v[134:135], v[40:41], v[50:51], v[134:135]
	v_cvt_pk_bf16_f32 v132, v132, v133
	v_cvt_pk_bf16_f32 v133, v134, v135
	global_store_dwordx2 v[0:1], v[132:133], off offset:16
	global_load_dwordx2 v[124:125], v[4:5], off offset:80
	global_load_dwordx2 v[126:127], v[6:7], off offset:80
	global_load_dwordx2 v[128:129], v[0:1], off offset:80
	global_load_dwordx4 v[132:135], v[12:13], off offset:160
	ds_read2st64_b32 v[40:41], v137 offset0:8 offset1:9
	ds_read2st64_b32 v[42:43], v137 offset0:10 offset1:11
	s_waitcnt vmcnt(14)
; DI unsigned pk2(float lo, float hi) { const f32x2_t v = {lo, hi}; const bf16x2_t b = __builtin_convertvector(v, bf16x2_t); return __builtin_bit_cast(unsigned, b); }
; DI float sigmoidf_(float x) { return __builtin_amdgcn_rcpf(1.f + __builtin_amdgcn_exp2f(fminf(-x * LOG2E, 126.f))); }
; template <int DV>
; DI void attn_unit(const int wv, const Args& A, LAS unsigned char* lds, int b, int g, int qb, int dry) {
;     ...
; #pragma unroll
;         for (int mt = 0; mt < 2; ++mt)
; #pragma unroll
;             for (int v = 0; v < 4; ++v) {
;                 const size_t idx = tokrow * DM + head * 64 + mt * 32 + 8 * v + 4 * c.h;
;                 const u32x2 yr = *(const u32x2*)(Yb + idx), gm = *(const u32x2*)(GMA + idx), ct = *(const u32x2*)((const bf16*)(ws + WS_CT) + idx);
;                 const f32x4 cr = *(const f32x4*)((const float*)(ws + WS_CARRY) + ((size_t)b * 64 + (c.t >> 7)) * DM + head * 64 + mt * 32 + 8 * v + 4 * c.h);
;                 const float o0 = bflo(yr.x) + bflo(ct.x) * cr[0] + sigmoidf_(bflo(gm.x)) * O[mt][4 * v], o1 = bfhi(yr.x) + bfhi(ct.x) * cr[1] + sigmoidf_(bfhi(gm.x)) * O[mt][4 * v + 1];
;                 const float o2 = bflo(yr.y) + bflo(ct.y) * cr[2] + sigmoidf_(bflo(gm.y)) * O[mt][4 * v + 2], o3 = bfhi(yr.y) + bfhi(ct.y) * cr[3] + sigmoidf_(bfhi(gm.y)) * O[mt][4 * v + 3];
;                 *(u32x2*)(((dry & 1) ? (bf16*)(ws + 832 * MiB) : Yb) + idx) = (u32x2){pk2(o0, o1), pk2(o2, o3)};
	v_lshlrev_b32_e32 v3, 16, v232
	v_and_b32_e32 v9, 0xffff0000, v232
	v_lshlrev_b32_e32 v38, 16, v233
	v_and_b32_e32 v39, 0xffff0000, v233
	v_mul_f32_e32 v3, 0xbfb8aa3b, v3
	v_mul_f32_e32 v9, 0xbfb8aa3b, v9
	v_mul_f32_e32 v38, 0xbfb8aa3b, v38
	v_mul_f32_e32 v39, 0xbfb8aa3b, v39
	v_min_f32_e32 v3, 0x42fc0000, v3
	v_min_f32_e32 v9, 0x42fc0000, v9
	v_min_f32_e32 v38, 0x42fc0000, v38
	v_min_f32_e32 v39, 0x42fc0000, v39
	v_exp_f32_e32 v3, v3
	v_exp_f32_e32 v9, v9
	v_exp_f32_e32 v38, v38
	v_exp_f32_e32 v39, v39
	v_add_f32_e32 v3, 1.0, v3
	v_add_f32_e32 v9, 1.0, v9
	v_add_f32_e32 v50, 1.0, v38
	v_add_f32_e32 v51, 1.0, v39
	v_rcp_f32_e32 v38, v3
	v_rcp_f32_e32 v39, v9
	v_rcp_f32_e32 v50, v50
	v_rcp_f32_e32 v51, v51
	v_lshlrev_b32_e32 v48, 16, v234
	v_and_b32_e32 v49, 0xffff0000, v234
	v_lshlrev_b32_e32 v36, 16, v235
	v_and_b32_e32 v37, 0xffff0000, v235
	v_lshlrev_b32_e32 v44, 16, v236
	v_and_b32_e32 v45, 0xffff0000, v236
	v_lshlrev_b32_e32 v46, 16, v237
	v_and_b32_e32 v47, 0xffff0000, v237
	s_waitcnt lgkmcnt(0)
	v_pk_fma_f32 v[34:35], v[8:9], v[72:73], v[40:41] op_sel_hi:[0,1,1]
	v_pk_fma_f32 v[40:41], v[8:9], v[74:75], v[42:43] op_sel_hi:[0,1,1]
	v_pk_fma_f32 v[240:241], v[240:241], v[48:49], v[44:45]
	v_pk_fma_f32 v[242:243], v[242:243], v[36:37], v[46:47]
	v_pk_fma_f32 v[240:241], v[34:35], v[38:39], v[240:241]
	v_pk_fma_f32 v[242:243], v[40:41], v[50:51], v[242:243]
	v_cvt_pk_bf16_f32 v240, v240, v241
	v_cvt_pk_bf16_f32 v241, v242, v243
	global_store_dwordx2 v[0:1], v[240:241], off offset:32
	global_load_dwordx2 v[232:233], v[4:5], off offset:96
	global_load_dwordx2 v[234:235], v[6:7], off offset:96
	global_load_dwordx2 v[236:237], v[0:1], off offset:96
	global_load_dwordx4 v[240:243], v[12:13], off offset:192
	ds_read2st64_b32 v[40:41], v137 offset0:12 offset1:13
	ds_read2st64_b32 v[42:43], v137 offset0:14 offset1:15
	s_waitcnt vmcnt(15)
	v_lshlrev_b32_e32 v3, 16, v244
	v_and_b32_e32 v9, 0xffff0000, v244
	v_lshlrev_b32_e32 v38, 16, v245
	v_and_b32_e32 v39, 0xffff0000, v245
	v_mul_f32_e32 v3, 0xbfb8aa3b, v3
	v_mul_f32_e32 v9, 0xbfb8aa3b, v9
	v_mul_f32_e32 v38, 0xbfb8aa3b, v38
	v_mul_f32_e32 v39, 0xbfb8aa3b, v39
	v_min_f32_e32 v3, 0x42fc0000, v3
	v_min_f32_e32 v9, 0x42fc0000, v9
	v_min_f32_e32 v38, 0x42fc0000, v38
	v_min_f32_e32 v39, 0x42fc0000, v39
	v_exp_f32_e32 v3, v3
	v_exp_f32_e32 v9, v9
	v_exp_f32_e32 v38, v38
	v_exp_f32_e32 v39, v39
	v_add_f32_e32 v3, 1.0, v3
	v_add_f32_e32 v9, 1.0, v9
	v_add_f32_e32 v50, 1.0, v38
	v_add_f32_e32 v51, 1.0, v39
	v_rcp_f32_e32 v38, v3
	v_rcp_f32_e32 v39, v9
	v_rcp_f32_e32 v50, v50
	v_rcp_f32_e32 v51, v51
	v_lshlrev_b32_e32 v48, 16, v246
	v_and_b32_e32 v49, 0xffff0000, v246
	v_lshlrev_b32_e32 v36, 16, v247
	v_and_b32_e32 v37, 0xffff0000, v247
	v_lshlrev_b32_e32 v44, 16, v248
	v_and_b32_e32 v45, 0xffff0000, v248
	v_lshlrev_b32_e32 v46, 16, v249
	v_and_b32_e32 v47, 0xffff0000, v249
	s_waitcnt lgkmcnt(0)
	v_pk_fma_f32 v[34:35], v[8:9], v[76:77], v[40:41] op_sel_hi:[0,1,1]
	v_pk_fma_f32 v[40:41], v[8:9], v[78:79], v[42:43] op_sel_hi:[0,1,1]
	v_pk_fma_f32 v[250:251], v[250:251], v[48:49], v[44:45]
	v_pk_fma_f32 v[252:253], v[252:253], v[36:37], v[46:47]
	v_pk_fma_f32 v[250:251], v[34:35], v[38:39], v[250:251]
	v_pk_fma_f32 v[252:253], v[40:41], v[50:51], v[252:253]
	v_cvt_pk_bf16_f32 v250, v250, v251
	v_cvt_pk_bf16_f32 v251, v252, v253
	global_store_dwordx2 v[0:1], v[250:251], off offset:48
	global_load_dwordx2 v[244:245], v[4:5], off offset:112
	global_load_dwordx2 v[246:247], v[6:7], off offset:112
	global_load_dwordx2 v[248:249], v[0:1], off offset:112
	global_load_dwordx4 v[250:253], v[12:13], off offset:224
	ds_read2st64_b32 v[40:41], v137 offset0:16 offset1:17
	ds_read2st64_b32 v[42:43], v137 offset0:18 offset1:19
	s_waitcnt vmcnt(15)
	v_lshlrev_b32_e32 v3, 16, v112
	v_and_b32_e32 v9, 0xffff0000, v112
	v_lshlrev_b32_e32 v38, 16, v113
	v_and_b32_e32 v39, 0xffff0000, v113
	v_mul_f32_e32 v3, 0xbfb8aa3b, v3
	v_mul_f32_e32 v9, 0xbfb8aa3b, v9
	v_mul_f32_e32 v38, 0xbfb8aa3b, v38
	v_mul_f32_e32 v39, 0xbfb8aa3b, v39
	v_min_f32_e32 v3, 0x42fc0000, v3
	v_min_f32_e32 v9, 0x42fc0000, v9
	v_min_f32_e32 v38, 0x42fc0000, v38
	v_min_f32_e32 v39, 0x42fc0000, v39
	v_exp_f32_e32 v3, v3
	v_exp_f32_e32 v9, v9
	v_exp_f32_e32 v38, v38
	v_exp_f32_e32 v39, v39
	v_add_f32_e32 v3, 1.0, v3
	v_add_f32_e32 v9, 1.0, v9
	v_add_f32_e32 v50, 1.0, v38
	v_add_f32_e32 v51, 1.0, v39
	v_rcp_f32_e32 v38, v3
	v_rcp_f32_e32 v39, v9
	v_rcp_f32_e32 v50, v50
	v_rcp_f32_e32 v51, v51
	v_lshlrev_b32_e32 v48, 16, v114
	v_and_b32_e32 v49, 0xffff0000, v114
	v_lshlrev_b32_e32 v36, 16, v115
	v_and_b32_e32 v37, 0xffff0000, v115
	v_lshlrev_b32_e32 v44, 16, v116
	v_and_b32_e32 v45, 0xffff0000, v116
	v_lshlrev_b32_e32 v46, 16, v117
	v_and_b32_e32 v47, 0xffff0000, v117
	s_waitcnt lgkmcnt(0)
	v_pk_fma_f32 v[34:35], v[8:9], v[16:17], v[40:41] op_sel_hi:[0,1,1]
	v_pk_fma_f32 v[40:41], v[8:9], v[18:19], v[42:43] op_sel_hi:[0,1,1]
	v_pk_fma_f32 v[120:121], v[120:121], v[48:49], v[44:45]
	v_pk_fma_f32 v[122:123], v[122:123], v[36:37], v[46:47]
	v_pk_fma_f32 v[120:121], v[34:35], v[38:39], v[120:121]
	v_pk_fma_f32 v[122:123], v[40:41], v[50:51], v[122:123]
	v_cvt_pk_bf16_f32 v120, v120, v121
	v_cvt_pk_bf16_f32 v121, v122, v123
	global_store_dwordx2 v[0:1], v[120:121], off offset:64
	ds_read2st64_b32 v[40:41], v137 offset0:20 offset1:21
	ds_read2st64_b32 v[42:43], v137 offset0:22 offset1:23
	s_waitcnt vmcnt(11)
; DI unsigned pk2(float lo, float hi) { const f32x2_t v = {lo, hi}; const bf16x2_t b = __builtin_convertvector(v, bf16x2_t); return __builtin_bit_cast(unsigned, b); }
; DI float sigmoidf_(float x) { return __builtin_amdgcn_rcpf(1.f + __builtin_amdgcn_exp2f(fminf(-x * LOG2E, 126.f))); }
; template <int DV>
; DI void attn_unit(const int wv, const Args& A, LAS unsigned char* lds, int b, int g, int qb, int dry) {
;     ...
; #pragma unroll
;         for (int mt = 0; mt < 2; ++mt)
; #pragma unroll
;             for (int v = 0; v < 4; ++v) {
;                 const size_t idx = tokrow * DM + head * 64 + mt * 32 + 8 * v + 4 * c.h;
;                 const u32x2 yr = *(const u32x2*)(Yb + idx), gm = *(const u32x2*)(GMA + idx), ct = *(const u32x2*)((const bf16*)(ws + WS_CT) + idx);
;                 const f32x4 cr = *(const f32x4*)((const float*)(ws + WS_CARRY) + ((size_t)b * 64 + (c.t >> 7)) * DM + head * 64 + mt * 32 + 8 * v + 4 * c.h);
;                 const float o0 = bflo(yr.x) + bflo(ct.x) * cr[0] + sigmoidf_(bflo(gm.x)) * O[mt][4 * v], o1 = bfhi(yr.x) + bfhi(ct.x) * cr[1] + sigmoidf_(bfhi(gm.x)) * O[mt][4 * v + 1];
;                 const float o2 = bflo(yr.y) + bflo(ct.y) * cr[2] + sigmoidf_(bflo(gm.y)) * O[mt][4 * v + 2], o3 = bfhi(yr.y) + bfhi(ct.y) * cr[3] + sigmoidf_(bfhi(gm.y)) * O[mt][4 * v + 3];
;                 *(u32x2*)(((dry & 1) ? (bf16*)(ws + 832 * MiB) : Yb) + idx) = (u32x2){pk2(o0, o1), pk2(o2, o3)};
	v_lshlrev_b32_e32 v3, 16, v124
	v_and_b32_e32 v9, 0xffff0000, v124
	v_lshlrev_b32_e32 v38, 16, v125
	v_and_b32_e32 v39, 0xffff0000, v125
	v_mul_f32_e32 v3, 0xbfb8aa3b, v3
	v_mul_f32_e32 v9, 0xbfb8aa3b, v9
	v_mul_f32_e32 v38, 0xbfb8aa3b, v38
	v_mul_f32_e32 v39, 0xbfb8aa3b, v39
	v_min_f32_e32 v3, 0x42fc0000, v3
	v_min_f32_e32 v9, 0x42fc0000, v9
	v_min_f32_e32 v38, 0x42fc0000, v38
	v_min_f32_e32 v39, 0x42fc0000, v39
	v_exp_f32_e32 v3, v3
	v_exp_f32_e32 v9, v9
	v_exp_f32_e32 v38, v38
	v_exp_f32_e32 v39, v39
	v_add_f32_e32 v3, 1.0, v3
	v_add_f32_e32 v9, 1.0, v9
	v_add_f32_e32 v50, 1.0, v38
	v_add_f32_e32 v51, 1.0, v39
	v_rcp_f32_e32 v38, v3
	v_rcp_f32_e32 v39, v9
	v_rcp_f32_e32 v50, v50
	v_rcp_f32_e32 v51, v51
	v_lshlrev_b32_e32 v48, 16, v126
	v_and_b32_e32 v49, 0xffff0000, v126
	v_lshlrev_b32_e32 v36, 16, v127
	v_and_b32_e32 v37, 0xffff0000, v127
	v_lshlrev_b32_e32 v44, 16, v128
	v_and_b32_e32 v45, 0xffff0000, v128
	v_lshlrev_b32_e32 v46, 16, v129
	v_and_b32_e32 v47, 0xffff0000, v129
	s_waitcnt lgkmcnt(0)
	v_pk_fma_f32 v[34:35], v[8:9], v[20:21], v[40:41] op_sel_hi:[0,1,1]
	v_pk_fma_f32 v[40:41], v[8:9], v[22:23], v[42:43] op_sel_hi:[0,1,1]
	v_pk_fma_f32 v[132:133], v[132:133], v[48:49], v[44:45]
	v_pk_fma_f32 v[134:135], v[134:135], v[36:37], v[46:47]
	v_pk_fma_f32 v[132:133], v[34:35], v[38:39], v[132:133]
	v_pk_fma_f32 v[134:135], v[40:41], v[50:51], v[134:135]
	v_cvt_pk_bf16_f32 v132, v132, v133
	v_cvt_pk_bf16_f32 v133, v134, v135
	global_store_dwordx2 v[0:1], v[132:133], off offset:80
	ds_read2st64_b32 v[40:41], v137 offset0:24 offset1:25
	ds_read2st64_b32 v[42:43], v137 offset0:26 offset1:27
	s_waitcnt vmcnt(7)
	v_lshlrev_b32_e32 v3, 16, v232
	v_and_b32_e32 v9, 0xffff0000, v232
	v_lshlrev_b32_e32 v38, 16, v233
	v_and_b32_e32 v39, 0xffff0000, v233
	v_mul_f32_e32 v3, 0xbfb8aa3b, v3
	v_mul_f32_e32 v9, 0xbfb8aa3b, v9
	v_mul_f32_e32 v38, 0xbfb8aa3b, v38
	v_mul_f32_e32 v39, 0xbfb8aa3b, v39
	v_min_f32_e32 v3, 0x42fc0000, v3
	v_min_f32_e32 v9, 0x42fc0000, v9
	v_min_f32_e32 v38, 0x42fc0000, v38
	v_min_f32_e32 v39, 0x42fc0000, v39
	v_exp_f32_e32 v3, v3
	v_exp_f32_e32 v9, v9
	v_exp_f32_e32 v38, v38
	v_exp_f32_e32 v39, v39
	v_add_f32_e32 v3, 1.0, v3
	v_add_f32_e32 v9, 1.0, v9
	v_add_f32_e32 v50, 1.0, v38
	v_add_f32_e32 v51, 1.0, v39
	v_rcp_f32_e32 v38, v3
	v_rcp_f32_e32 v39, v9
	v_rcp_f32_e32 v50, v50
	v_rcp_f32_e32 v51, v51
	v_lshlrev_b32_e32 v48, 16, v234
	v_and_b32_e32 v49, 0xffff0000, v234
	v_lshlrev_b32_e32 v36, 16, v235
	v_and_b32_e32 v37, 0xffff0000, v235
	v_lshlrev_b32_e32 v44, 16, v236
	v_and_b32_e32 v45, 0xffff0000, v236
	v_lshlrev_b32_e32 v46, 16, v237
	v_and_b32_e32 v47, 0xffff0000, v237
	s_waitcnt lgkmcnt(0)
	v_pk_fma_f32 v[34:35], v[8:9], v[24:25], v[40:41] op_sel_hi:[0,1,1]
	v_pk_fma_f32 v[40:41], v[8:9], v[26:27], v[42:43] op_sel_hi:[0,1,1]
	v_pk_fma_f32 v[240:241], v[240:241], v[48:49], v[44:45]
	v_pk_fma_f32 v[242:243], v[242:243], v[36:37], v[46:47]
	v_pk_fma_f32 v[240:241], v[34:35], v[38:39], v[240:241]
	v_pk_fma_f32 v[242:243], v[40:41], v[50:51], v[242:243]
	v_cvt_pk_bf16_f32 v240, v240, v241
	v_cvt_pk_bf16_f32 v241, v242, v243
	global_store_dwordx2 v[0:1], v[240:241], off offset:96
	ds_read2st64_b32 v[40:41], v137 offset0:28 offset1:29
	ds_read2st64_b32 v[42:43], v137 offset0:30 offset1:31
	s_waitcnt vmcnt(3)
	v_lshlrev_b32_e32 v3, 16, v244
	v_and_b32_e32 v9, 0xffff0000, v244
	v_lshlrev_b32_e32 v38, 16, v245
	v_and_b32_e32 v39, 0xffff0000, v245
	v_mul_f32_e32 v3, 0xbfb8aa3b, v3
	v_mul_f32_e32 v9, 0xbfb8aa3b, v9
	v_mul_f32_e32 v38, 0xbfb8aa3b, v38
	v_mul_f32_e32 v39, 0xbfb8aa3b, v39
	v_min_f32_e32 v3, 0x42fc0000, v3
	v_min_f32_e32 v9, 0x42fc0000, v9
	v_min_f32_e32 v38, 0x42fc0000, v38
	v_min_f32_e32 v39, 0x42fc0000, v39
	v_exp_f32_e32 v3, v3
	v_exp_f32_e32 v9, v9
	v_exp_f32_e32 v38, v38
	v_exp_f32_e32 v39, v39
	v_add_f32_e32 v3, 1.0, v3
	v_add_f32_e32 v9, 1.0, v9
	v_add_f32_e32 v50, 1.0, v38
	v_add_f32_e32 v51, 1.0, v39
	v_rcp_f32_e32 v38, v3
	v_rcp_f32_e32 v39, v9
	v_rcp_f32_e32 v50, v50
	v_rcp_f32_e32 v51, v51
	v_lshlrev_b32_e32 v48, 16, v246
	v_and_b32_e32 v49, 0xffff0000, v246
	v_lshlrev_b32_e32 v36, 16, v247
	v_and_b32_e32 v37, 0xffff0000, v247
	v_lshlrev_b32_e32 v44, 16, v248
	v_and_b32_e32 v45, 0xffff0000, v248
	v_lshlrev_b32_e32 v46, 16, v249
	v_and_b32_e32 v47, 0xffff0000, v249
	s_waitcnt lgkmcnt(0)
	v_pk_fma_f32 v[34:35], v[8:9], v[28:29], v[40:41] op_sel_hi:[0,1,1]
	v_pk_fma_f32 v[40:41], v[8:9], v[30:31], v[42:43] op_sel_hi:[0,1,1]
	v_pk_fma_f32 v[250:251], v[250:251], v[48:49], v[44:45]
	v_pk_fma_f32 v[252:253], v[252:253], v[36:37], v[46:47]
	v_pk_fma_f32 v[250:251], v[34:35], v[38:39], v[250:251]
	v_pk_fma_f32 v[252:253], v[40:41], v[50:51], v[252:253]
	v_cvt_pk_bf16_f32 v250, v250, v251
	v_cvt_pk_bf16_f32 v251, v252, v253
	global_store_dwordx2 v[0:1], v[250:251], off offset:112
